# same as previous but the two GEMM loops this grid never runs (DFTQ, non-merged DFTS) left as baseline code
# baseline (speedup 1.0000x reference)
.LBB0_35:
	s_add_u32 s0, s8, 0xfff80080
	s_addc_u32 s1, s9, -1
	s_add_i32 s2, 0, 0x10000
	v_add_u32_e32 v138, s2, v182
	ds_read_b128 v[154:157], v138
	ds_read_b128 v[158:161], v138 offset:1024
	ds_read_b128 v[162:165], v138 offset:2048
	ds_read_b128 v[166:169], v138 offset:3072
	s_cmp_eq_u32 s15, 28
	s_cselect_b32 s65, s67, s1
	s_cselect_b32 s64, s66, s0
	s_cselect_b32 s1, s45, s13
	s_cselect_b32 s0, s44, s11
	v_lshl_add_u64 v[138:139], s[8:9], 0, v[136:137]
	s_add_i32 m0, s17, 0xc000
	ds_read_b128 v[170:173], v183
	ds_read_b128 v[174:177], v183 offset:1024
	ds_read_b128 v[178:181], v183 offset:2048
	ds_read_b128 v[184:187], v183 offset:3072
	ds_read_b128 v[188:191], v183 offset:4096
	ds_read_b128 v[192:195], v183 offset:5120
	ds_read_b128 v[196:199], v183 offset:6144
	ds_read_b128 v[200:203], v183 offset:7168
	global_load_lds_dwordx4 v[138:139], off
	v_lshl_add_u64 v[138:139], s[8:9], 0, v[134:135]
	s_add_i32 m0, s17, 0xe000
	s_nop 0
	global_load_lds_dwordx4 v[138:139], off
	s_waitcnt lgkmcnt(8)
	s_barrier
	s_waitcnt lgkmcnt(0)
	s_setprio 1
	v_mfma_f32_16x16x32_bf16 v[124:127], v[154:157], v[170:173], v[124:127]
	v_mfma_f32_16x16x32_bf16 v[92:95], v[162:165], v[170:173], v[92:95]
	v_mfma_f32_16x16x32_bf16 v[120:123], v[154:157], v[178:181], v[120:123]
	v_mfma_f32_16x16x32_bf16 v[88:91], v[162:165], v[178:181], v[88:91]
	v_mfma_f32_16x16x32_bf16 v[116:119], v[154:157], v[188:191], v[116:119]
	v_mfma_f32_16x16x32_bf16 v[84:87], v[162:165], v[188:191], v[84:87]
	v_mfma_f32_16x16x32_bf16 v[112:115], v[154:157], v[196:199], v[112:115]
	v_mfma_f32_16x16x32_bf16 v[80:83], v[162:165], v[196:199], v[80:83]
	v_mfma_f32_16x16x32_bf16 v[124:127], v[158:161], v[174:177], v[124:127]
	v_mfma_f32_16x16x32_bf16 v[92:95], v[166:169], v[174:177], v[92:95]
	v_mfma_f32_16x16x32_bf16 v[120:123], v[158:161], v[184:187], v[120:123]
	v_mfma_f32_16x16x32_bf16 v[88:91], v[166:169], v[184:187], v[88:91]
	v_mfma_f32_16x16x32_bf16 v[116:119], v[158:161], v[192:195], v[116:119]
	v_mfma_f32_16x16x32_bf16 v[84:87], v[166:169], v[192:195], v[84:87]
	v_mfma_f32_16x16x32_bf16 v[112:115], v[158:161], v[200:203], v[112:115]
	v_mfma_f32_16x16x32_bf16 v[80:83], v[166:169], v[200:203], v[80:83]
	s_setprio 0
	s_barrier
	s_add_i32 s20, 0, 0x14000
	v_add_u32_e32 v138, s20, v182
	s_add_i32 s2, s2, s69
	ds_read_b128 v[204:207], v138
	ds_read_b128 v[208:211], v138 offset:1024
	ds_read_b128 v[228:231], v138 offset:2048
	ds_read_b128 v[232:235], v138 offset:3072
	v_lshl_add_u64 v[138:139], s[0:1], 0, v[140:141]
	s_mov_b32 m0, s2
	v_lshl_add_u64 v[236:237], s[0:1], 0, v[132:133]
	global_load_lds_dwordx4 v[138:139], off
	s_add_i32 m0, s2, 0x2000
	s_nop 0
	global_load_lds_dwordx4 v[236:237], off
	s_barrier
	s_waitcnt lgkmcnt(0)
	s_setprio 1
	v_mfma_f32_16x16x32_bf16 v[60:63], v[204:207], v[170:173], v[60:63]
	v_mfma_f32_16x16x32_bf16 v[28:31], v[228:231], v[170:173], v[28:31]
	v_mfma_f32_16x16x32_bf16 v[56:59], v[204:207], v[178:181], v[56:59]
	v_mfma_f32_16x16x32_bf16 v[24:27], v[228:231], v[178:181], v[24:27]
	v_mfma_f32_16x16x32_bf16 v[52:55], v[204:207], v[188:191], v[52:55]
	v_mfma_f32_16x16x32_bf16 v[20:23], v[228:231], v[188:191], v[20:23]
	v_mfma_f32_16x16x32_bf16 v[48:51], v[204:207], v[196:199], v[48:51]
	v_mfma_f32_16x16x32_bf16 v[16:19], v[228:231], v[196:199], v[16:19]
	v_mfma_f32_16x16x32_bf16 v[60:63], v[208:211], v[174:177], v[60:63]
	v_mfma_f32_16x16x32_bf16 v[28:31], v[232:235], v[174:177], v[28:31]
	v_mfma_f32_16x16x32_bf16 v[56:59], v[208:211], v[184:187], v[56:59]
	v_mfma_f32_16x16x32_bf16 v[24:27], v[232:235], v[184:187], v[24:27]
	v_mfma_f32_16x16x32_bf16 v[52:55], v[208:211], v[192:195], v[52:55]
	v_mfma_f32_16x16x32_bf16 v[20:23], v[232:235], v[192:195], v[20:23]
	v_mfma_f32_16x16x32_bf16 v[48:51], v[208:211], v[200:203], v[48:51]
	v_mfma_f32_16x16x32_bf16 v[16:19], v[232:235], v[200:203], v[16:19]
	s_setprio 0
	s_mov_b32 m0, s17
	v_lshl_add_u64 v[238:239], s[64:65], 0, v[128:129]
	s_barrier
	ds_read_b128 v[170:173], v183 offset:16384
	ds_read_b128 v[174:177], v183 offset:17408
	ds_read_b128 v[178:181], v183 offset:18432
	ds_read_b128 v[184:187], v183 offset:19456
	ds_read_b128 v[188:191], v183 offset:20480
	ds_read_b128 v[192:195], v183 offset:21504
	ds_read_b128 v[196:199], v183 offset:22528
	ds_read_b128 v[200:203], v183 offset:23552
	global_load_lds_dwordx4 v[238:239], off
	v_lshl_add_u64 v[240:241], s[64:65], 0, v[130:131]
	s_mov_b32 m0, s71
	s_nop 0
	global_load_lds_dwordx4 v[240:241], off
	s_barrier
	s_waitcnt lgkmcnt(0)
	s_setprio 1
	v_mfma_f32_16x16x32_bf16 v[108:111], v[154:157], v[170:173], v[108:111]
	v_mfma_f32_16x16x32_bf16 v[76:79], v[162:165], v[170:173], v[76:79]
	v_mfma_f32_16x16x32_bf16 v[104:107], v[154:157], v[178:181], v[104:107]
	v_mfma_f32_16x16x32_bf16 v[72:75], v[162:165], v[178:181], v[72:75]
	v_mfma_f32_16x16x32_bf16 v[100:103], v[154:157], v[188:191], v[100:103]
	v_mfma_f32_16x16x32_bf16 v[68:71], v[162:165], v[188:191], v[68:71]
	v_mfma_f32_16x16x32_bf16 v[96:99], v[154:157], v[196:199], v[96:99]
	v_mfma_f32_16x16x32_bf16 v[64:67], v[162:165], v[196:199], v[64:67]
	v_mfma_f32_16x16x32_bf16 v[108:111], v[158:161], v[174:177], v[108:111]
	v_mfma_f32_16x16x32_bf16 v[76:79], v[166:169], v[174:177], v[76:79]
	v_mfma_f32_16x16x32_bf16 v[104:107], v[158:161], v[184:187], v[104:107]
	v_mfma_f32_16x16x32_bf16 v[72:75], v[166:169], v[184:187], v[72:75]
	v_mfma_f32_16x16x32_bf16 v[100:103], v[158:161], v[192:195], v[100:103]
	v_mfma_f32_16x16x32_bf16 v[68:71], v[166:169], v[192:195], v[68:71]
	v_mfma_f32_16x16x32_bf16 v[96:99], v[158:161], v[200:203], v[96:99]
	v_mfma_f32_16x16x32_bf16 v[64:67], v[166:169], v[200:203], v[64:67]
	s_setprio 0
	s_barrier
	s_add_u32 s18, s0, 0x100000
	s_addc_u32 s19, s1, 0
	s_add_i32 s2, s20, s69
	v_lshl_add_u64 v[154:155], s[18:19], 0, v[140:141]
	s_mov_b32 m0, s2
	s_nop 0
	global_load_lds_dwordx4 v[154:155], off
	v_lshl_add_u64 v[154:155], s[18:19], 0, v[132:133]
	s_add_i32 m0, s2, 0x2000
	s_nop 0
	global_load_lds_dwordx4 v[154:155], off
	s_waitcnt vmcnt(6)
	s_barrier
	s_setprio 1
	v_mfma_f32_16x16x32_bf16 v[44:47], v[204:207], v[170:173], v[44:47]
	v_mfma_f32_16x16x32_bf16 v[12:15], v[228:231], v[170:173], v[12:15]
	v_mfma_f32_16x16x32_bf16 v[40:43], v[204:207], v[178:181], v[40:43]
	v_mfma_f32_16x16x32_bf16 v[8:11], v[228:231], v[178:181], v[8:11]
	v_mfma_f32_16x16x32_bf16 v[36:39], v[204:207], v[188:191], v[36:39]
	v_mfma_f32_16x16x32_bf16 v[4:7], v[228:231], v[188:191], v[4:7]
	v_mfma_f32_16x16x32_bf16 v[32:35], v[204:207], v[196:199], v[32:35]
	v_mfma_f32_16x16x32_bf16 v[0:3], v[228:231], v[196:199], v[0:3]
	v_mfma_f32_16x16x32_bf16 v[44:47], v[208:211], v[174:177], v[44:47]
	v_mfma_f32_16x16x32_bf16 v[12:15], v[232:235], v[174:177], v[12:15]
	v_mfma_f32_16x16x32_bf16 v[40:43], v[208:211], v[184:187], v[40:43]
	v_mfma_f32_16x16x32_bf16 v[8:11], v[232:235], v[184:187], v[8:11]
	v_mfma_f32_16x16x32_bf16 v[36:39], v[208:211], v[192:195], v[36:39]
	v_mfma_f32_16x16x32_bf16 v[4:7], v[232:235], v[192:195], v[4:7]
	v_mfma_f32_16x16x32_bf16 v[32:35], v[208:211], v[200:203], v[32:35]
	v_mfma_f32_16x16x32_bf16 v[0:3], v[232:235], v[200:203], v[0:3]
	s_setprio 0
	s_add_i32 s2, 0, 0x18000
	v_add_u32_e32 v166, s2, v182
	s_barrier
	ds_read_b128 v[154:157], v166
	ds_read_b128 v[158:161], v166 offset:1024
	ds_read_b128 v[162:165], v166 offset:2048
	ds_read_b128 v[166:169], v166 offset:3072
	s_add_u32 s18, s64, 0x80000
	s_addc_u32 s19, s65, 0
	s_mov_b32 m0, s72
	v_lshl_add_u64 v[204:205], s[18:19], 0, v[128:129]
	ds_read_b128 v[170:173], v183 offset:32768
	ds_read_b128 v[174:177], v183 offset:33792
	ds_read_b128 v[178:181], v183 offset:34816
	ds_read_b128 v[184:187], v183 offset:35840
	ds_read_b128 v[188:191], v183 offset:36864
	ds_read_b128 v[192:195], v183 offset:37888
	ds_read_b128 v[196:199], v183 offset:38912
	ds_read_b128 v[200:203], v183 offset:39936
	global_load_lds_dwordx4 v[204:205], off
	v_lshl_add_u64 v[204:205], s[18:19], 0, v[130:131]
	s_mov_b32 m0, s73
	s_nop 0
	global_load_lds_dwordx4 v[204:205], off
	s_waitcnt lgkmcnt(8)
	s_barrier
	s_waitcnt lgkmcnt(0)
	s_setprio 1
	v_mfma_f32_16x16x32_bf16 v[124:127], v[154:157], v[170:173], v[124:127]
	v_mfma_f32_16x16x32_bf16 v[92:95], v[162:165], v[170:173], v[92:95]
	v_mfma_f32_16x16x32_bf16 v[120:123], v[154:157], v[178:181], v[120:123]
	v_mfma_f32_16x16x32_bf16 v[88:91], v[162:165], v[178:181], v[88:91]
	v_mfma_f32_16x16x32_bf16 v[116:119], v[154:157], v[188:191], v[116:119]
	v_mfma_f32_16x16x32_bf16 v[84:87], v[162:165], v[188:191], v[84:87]
	v_mfma_f32_16x16x32_bf16 v[112:115], v[154:157], v[196:199], v[112:115]
	v_mfma_f32_16x16x32_bf16 v[80:83], v[162:165], v[196:199], v[80:83]
	v_mfma_f32_16x16x32_bf16 v[124:127], v[158:161], v[174:177], v[124:127]
	v_mfma_f32_16x16x32_bf16 v[92:95], v[166:169], v[174:177], v[92:95]
	v_mfma_f32_16x16x32_bf16 v[120:123], v[158:161], v[184:187], v[120:123]
	v_mfma_f32_16x16x32_bf16 v[88:91], v[166:169], v[184:187], v[88:91]
	v_mfma_f32_16x16x32_bf16 v[116:119], v[158:161], v[192:195], v[116:119]
	v_mfma_f32_16x16x32_bf16 v[84:87], v[166:169], v[192:195], v[84:87]
	v_mfma_f32_16x16x32_bf16 v[112:115], v[158:161], v[200:203], v[112:115]
	v_mfma_f32_16x16x32_bf16 v[80:83], v[166:169], v[200:203], v[80:83]
	s_setprio 0
	s_barrier
	s_add_i32 s18, 0, 0x1c000
	s_add_i32 s2, s2, s69
	v_add_u32_e32 v232, s18, v182
	v_lshl_add_u64 v[138:139], v[138:139], 0, s[82:83]
	s_mov_b32 m0, s2
	ds_read_b128 v[204:207], v232
	ds_read_b128 v[208:211], v232 offset:1024
	ds_read_b128 v[228:231], v232 offset:2048
	ds_read_b128 v[232:235], v232 offset:3072
	global_load_lds_dwordx4 v[138:139], off
	v_lshl_add_u64 v[138:139], v[236:237], 0, s[82:83]
	s_add_i32 m0, s2, 0x2000
	s_nop 0
	global_load_lds_dwordx4 v[138:139], off
	s_barrier
	s_waitcnt lgkmcnt(0)
	s_setprio 1
	v_mfma_f32_16x16x32_bf16 v[60:63], v[204:207], v[170:173], v[60:63]
	v_mfma_f32_16x16x32_bf16 v[28:31], v[228:231], v[170:173], v[28:31]
	v_mfma_f32_16x16x32_bf16 v[56:59], v[204:207], v[178:181], v[56:59]
	v_mfma_f32_16x16x32_bf16 v[24:27], v[228:231], v[178:181], v[24:27]
	v_mfma_f32_16x16x32_bf16 v[52:55], v[204:207], v[188:191], v[52:55]
	v_mfma_f32_16x16x32_bf16 v[20:23], v[228:231], v[188:191], v[20:23]
	v_mfma_f32_16x16x32_bf16 v[48:51], v[204:207], v[196:199], v[48:51]
	v_mfma_f32_16x16x32_bf16 v[16:19], v[228:231], v[196:199], v[16:19]
	v_mfma_f32_16x16x32_bf16 v[60:63], v[208:211], v[174:177], v[60:63]
	v_mfma_f32_16x16x32_bf16 v[28:31], v[232:235], v[174:177], v[28:31]
	v_mfma_f32_16x16x32_bf16 v[56:59], v[208:211], v[184:187], v[56:59]
	v_mfma_f32_16x16x32_bf16 v[24:27], v[232:235], v[184:187], v[24:27]
	v_mfma_f32_16x16x32_bf16 v[52:55], v[208:211], v[192:195], v[52:55]
	v_mfma_f32_16x16x32_bf16 v[20:23], v[232:235], v[192:195], v[20:23]
	v_mfma_f32_16x16x32_bf16 v[48:51], v[208:211], v[200:203], v[48:51]
	v_mfma_f32_16x16x32_bf16 v[16:19], v[232:235], v[200:203], v[16:19]
	s_setprio 0
	s_mov_b32 m0, s77
	v_lshl_add_u64 v[138:139], v[238:239], 0, s[82:83]
	s_barrier
	ds_read_b128 v[170:173], v183 offset:49152
	ds_read_b128 v[174:177], v183 offset:50176
	ds_read_b128 v[178:181], v183 offset:51200
	ds_read_b128 v[184:187], v183 offset:52224
	ds_read_b128 v[188:191], v183 offset:53248
	ds_read_b128 v[192:195], v183 offset:54272
	ds_read_b128 v[196:199], v183 offset:55296
	ds_read_b128 v[200:203], v183 offset:56320
	global_load_lds_dwordx4 v[138:139], off
	v_lshl_add_u64 v[138:139], v[240:241], 0, s[82:83]
	s_mov_b32 m0, s80
	s_nop 0
	global_load_lds_dwordx4 v[138:139], off
	s_barrier
	s_waitcnt lgkmcnt(0)
	s_setprio 1
	v_mfma_f32_16x16x32_bf16 v[108:111], v[154:157], v[170:173], v[108:111]
	v_mfma_f32_16x16x32_bf16 v[76:79], v[162:165], v[170:173], v[76:79]
	v_mfma_f32_16x16x32_bf16 v[104:107], v[154:157], v[178:181], v[104:107]
	v_mfma_f32_16x16x32_bf16 v[72:75], v[162:165], v[178:181], v[72:75]
	v_mfma_f32_16x16x32_bf16 v[100:103], v[154:157], v[188:191], v[100:103]
	v_mfma_f32_16x16x32_bf16 v[68:71], v[162:165], v[188:191], v[68:71]
	v_mfma_f32_16x16x32_bf16 v[96:99], v[154:157], v[196:199], v[96:99]
	v_mfma_f32_16x16x32_bf16 v[64:67], v[162:165], v[196:199], v[64:67]
	v_mfma_f32_16x16x32_bf16 v[108:111], v[158:161], v[174:177], v[108:111]
	v_mfma_f32_16x16x32_bf16 v[76:79], v[166:169], v[174:177], v[76:79]
	v_mfma_f32_16x16x32_bf16 v[104:107], v[158:161], v[184:187], v[104:107]
	v_mfma_f32_16x16x32_bf16 v[72:75], v[166:169], v[184:187], v[72:75]
	v_mfma_f32_16x16x32_bf16 v[100:103], v[158:161], v[192:195], v[100:103]
	v_mfma_f32_16x16x32_bf16 v[68:71], v[166:169], v[192:195], v[68:71]
	v_mfma_f32_16x16x32_bf16 v[96:99], v[158:161], v[200:203], v[96:99]
	v_mfma_f32_16x16x32_bf16 v[64:67], v[166:169], v[200:203], v[64:67]
	s_setprio 0
	s_barrier
	s_add_u32 s0, s0, 0x100080
	s_addc_u32 s1, s1, 0
	s_add_i32 s2, s18, s69
	v_lshl_add_u64 v[138:139], s[0:1], 0, v[140:141]
	s_mov_b32 m0, s2
	s_nop 0
	global_load_lds_dwordx4 v[138:139], off
	v_lshl_add_u64 v[138:139], s[0:1], 0, v[132:133]
	s_add_i32 m0, s2, 0x2000
	s_nop 0
	global_load_lds_dwordx4 v[138:139], off
	s_waitcnt vmcnt(6)
	s_barrier
	s_setprio 1
	v_mfma_f32_16x16x32_bf16 v[44:47], v[204:207], v[170:173], v[44:47]
	v_mfma_f32_16x16x32_bf16 v[12:15], v[228:231], v[170:173], v[12:15]
	v_mfma_f32_16x16x32_bf16 v[40:43], v[204:207], v[178:181], v[40:43]
	v_mfma_f32_16x16x32_bf16 v[8:11], v[228:231], v[178:181], v[8:11]
	v_mfma_f32_16x16x32_bf16 v[36:39], v[204:207], v[188:191], v[36:39]
	v_mfma_f32_16x16x32_bf16 v[4:7], v[228:231], v[188:191], v[4:7]
	v_mfma_f32_16x16x32_bf16 v[32:35], v[204:207], v[196:199], v[32:35]
	v_mfma_f32_16x16x32_bf16 v[0:3], v[228:231], v[196:199], v[0:3]
	v_mfma_f32_16x16x32_bf16 v[44:47], v[208:211], v[174:177], v[44:47]
	v_mfma_f32_16x16x32_bf16 v[12:15], v[232:235], v[174:177], v[12:15]
	v_mfma_f32_16x16x32_bf16 v[40:43], v[208:211], v[184:187], v[40:43]
	v_mfma_f32_16x16x32_bf16 v[8:11], v[232:235], v[184:187], v[8:11]
	v_mfma_f32_16x16x32_bf16 v[36:39], v[208:211], v[192:195], v[36:39]
	v_mfma_f32_16x16x32_bf16 v[4:7], v[232:235], v[192:195], v[4:7]
	v_mfma_f32_16x16x32_bf16 v[32:35], v[208:211], v[200:203], v[32:35]
	v_mfma_f32_16x16x32_bf16 v[0:3], v[232:235], v[200:203], v[0:3]
	s_setprio 0
	s_add_i32 s15, s15, 2
	s_add_u32 s11, s11, 0x100
	s_addc_u32 s13, s13, 0
	s_add_u32 s8, s8, 0x100
	s_addc_u32 s9, s9, 0
	s_cmp_gt_u32 s15, 29
	s_barrier
	s_cbranch_scc0 .LBB0_35
	v_mbcnt_lo_u32_b32 v170, -1, 0
	v_mbcnt_hi_u32_b32 v170, -1, v170
	s_lshl_b32 s0, s16, 8
	v_ashrrev_i32_e32 v138, 2, v170
	v_and_b32_e32 v138, -4, v138
	s_or_b32 s0, s0, s75
	v_add_u32_e32 v138, s0, v138
	s_lshl_b32 s0, s88, 10
	s_ashr_i32 s1, s0, 31
	s_lshl_b32 s13, s88, 12
	s_lshl_b32 s15, s88, 11
	s_addk_i32 s13, 0x1000
	s_lshl_b64 s[0:1], s[0:1], 2
	v_and_or_b32 v154, v170, 15, s74
	s_add_u32 s0, s49, s0
	v_ashrrev_i32_e32 v139, 31, v138
	v_lshl_add_u32 v184, s10, 8, v154
	s_addc_u32 s1, s76, s1
	v_lshlrev_b64 v[172:173], 2, v[138:139]
	v_add_u32_e32 v156, s15, v184
	v_lshl_add_u64 v[160:161], s[0:1], 0, v[172:173]
	v_ashrrev_i32_e32 v157, 31, v156
	flat_load_dwordx4 v[162:165], v[160:161]
	v_lshlrev_b64 v[154:155], 12, v[156:157]
	v_lshl_add_u64 v[154:155], s[26:27], 0, v[154:155]
	v_lshl_add_u64 v[158:159], v[154:155], 0, v[172:173]
	flat_load_dwordx4 v[166:169], v[158:159] nt
	s_mov_b32 s0, 0x3c800000
	v_and_b32_e32 v155, 1, v170
	v_add_u32_e32 v156, s15, v156
	v_cmp_eq_u32_e64 s[8:9], 0, v155
	v_ashrrev_i32_e32 v157, 31, v156
	v_lshlrev_b64 v[156:157], 11, v[156:157]
	v_sub_u32_e32 v154, s13, v184
	v_lshl_add_u64 v[156:157], s[24:25], 0, v[156:157]
	v_cmp_ne_u32_e32 vcc, 0, v184
	v_lshl_add_u64 v[156:157], v[138:139], 1, v[156:157]
	s_waitcnt vmcnt(0) lgkmcnt(0)
	v_pk_mul_f32 v[164:165], v[164:165], s[0:1] op_sel_hi:[1,0]
	v_pk_mul_f32 v[162:163], v[162:163], s[0:1] op_sel_hi:[1,0]
	v_xor_b32_e32 v170, 0x80000000, v164
	v_xor_b32_e32 v171, 0x80000000, v165
	v_xor_b32_e32 v174, 0x80000000, v162
	v_xor_b32_e32 v175, 0x80000000, v163
	v_cndmask_b32_e64 v177, v171, v165, s[8:9]
	v_cndmask_b32_e64 v176, v170, v164, s[8:9]
	v_cndmask_b32_e64 v179, v175, v163, s[8:9]
	v_cndmask_b32_e64 v178, v174, v162, s[8:9]
	v_pk_add_f32 v[162:163], v[168:169], v[176:177]
	v_pk_add_f32 v[164:165], v[166:167], v[178:179]
	v_sub_f32_e32 v155, v162, v126
	v_sub_f32_e32 v167, v163, v127
	v_sub_f32_e32 v166, v164, v124
	v_cvt_pk_bf16_f32 v167, v155, v167
	v_ashrrev_i32_e32 v155, 31, v154
	v_sub_f32_e32 v168, v165, v125
	v_cvt_pk_bf16_f32 v166, v166, v168
	flat_store_dwordx2 v[156:157], v[166:167]
	s_and_saveexec_b64 s[0:1], vcc
	s_cbranch_execz .LBB0_38
	v_pk_add_f32 v[126:127], v[126:127], v[162:163]
	v_pk_add_f32 v[124:125], v[124:125], v[164:165]
	s_nop 0
	v_cvt_pk_bf16_f32 v124, v124, v125
	v_cvt_pk_bf16_f32 v125, v126, v127
	v_lshlrev_b64 v[126:127], 11, v[154:155]
	v_lshl_add_u64 v[126:127], s[24:25], 0, v[126:127]
	v_lshl_add_u64 v[126:127], v[138:139], 1, v[126:127]
	flat_store_dwordx2 v[126:127], v[124:125]

.LBB0_169:
	s_add_u32 s0, s66, 0xfff80080
	s_addc_u32 s1, s67, -1
	s_add_i32 s2, 0, 0x10000
	v_add_u32_e32 v166, s2, v138
	ds_read_b128 v[154:157], v166
	ds_read_b128 v[158:161], v166 offset:1024
	ds_read_b128 v[162:165], v166 offset:2048
	ds_read_b128 v[166:169], v166 offset:3072
	s_cmp_eq_u32 s45, 28
	s_cselect_b32 s69, s9, s1
	s_cselect_b32 s68, s8, s0
	s_cselect_b32 s1, s65, s41
	s_cselect_b32 s0, s64, s17
	v_lshl_add_u64 v[202:203], s[66:67], 0, v[136:137]
	s_add_i32 m0, s11, 0xc000
	ds_read_b128 v[170:173], v139
	ds_read_b128 v[174:177], v139 offset:1024
	ds_read_b128 v[178:181], v139 offset:2048
	ds_read_b128 v[182:185], v139 offset:3072
	ds_read_b128 v[186:189], v139 offset:4096
	ds_read_b128 v[190:193], v139 offset:5120
	ds_read_b128 v[194:197], v139 offset:6144
	ds_read_b128 v[198:201], v139 offset:7168
	global_load_lds_dwordx4 v[202:203], off
	v_lshl_add_u64 v[202:203], s[66:67], 0, v[134:135]
	s_add_i32 m0, s11, 0xe000
	s_nop 0
	global_load_lds_dwordx4 v[202:203], off
	s_waitcnt lgkmcnt(8)
	s_barrier
	s_waitcnt lgkmcnt(0)
	s_setprio 1
	v_mfma_f32_16x16x32_bf16 v[124:127], v[154:157], v[170:173], v[124:127]
	v_mfma_f32_16x16x32_bf16 v[120:123], v[162:165], v[170:173], v[120:123]
	v_mfma_f32_16x16x32_bf16 v[116:119], v[154:157], v[178:181], v[116:119]
	v_mfma_f32_16x16x32_bf16 v[112:115], v[162:165], v[178:181], v[112:115]
	v_mfma_f32_16x16x32_bf16 v[104:107], v[154:157], v[186:189], v[104:107]
	v_mfma_f32_16x16x32_bf16 v[96:99], v[162:165], v[186:189], v[96:99]
	v_mfma_f32_16x16x32_bf16 v[88:91], v[154:157], v[194:197], v[88:91]
	v_mfma_f32_16x16x32_bf16 v[80:83], v[162:165], v[194:197], v[80:83]
	v_mfma_f32_16x16x32_bf16 v[124:127], v[158:161], v[174:177], v[124:127]
	v_mfma_f32_16x16x32_bf16 v[120:123], v[166:169], v[174:177], v[120:123]
	v_mfma_f32_16x16x32_bf16 v[116:119], v[158:161], v[182:185], v[116:119]
	v_mfma_f32_16x16x32_bf16 v[112:115], v[166:169], v[182:185], v[112:115]
	v_mfma_f32_16x16x32_bf16 v[104:107], v[158:161], v[190:193], v[104:107]
	v_mfma_f32_16x16x32_bf16 v[96:99], v[166:169], v[190:193], v[96:99]
	v_mfma_f32_16x16x32_bf16 v[88:91], v[158:161], v[198:201], v[88:91]
	v_mfma_f32_16x16x32_bf16 v[80:83], v[166:169], v[198:201], v[80:83]
	s_setprio 0
	s_barrier
	s_add_i32 s30, 0, 0x14000
	v_add_u32_e32 v210, s30, v138
	s_add_i32 s2, s2, s20
	ds_read_b128 v[202:205], v210
	ds_read_b128 v[206:209], v210 offset:1024
	ds_read_b128 v[228:231], v210 offset:2048
	ds_read_b128 v[232:235], v210 offset:3072
	v_lshl_add_u64 v[210:211], s[0:1], 0, v[140:141]
	s_mov_b32 m0, s2
	v_lshl_add_u64 v[236:237], s[0:1], 0, v[132:133]
	global_load_lds_dwordx4 v[210:211], off
	s_add_i32 m0, s2, 0x2000
	s_nop 0
	global_load_lds_dwordx4 v[236:237], off
	s_barrier
	s_waitcnt lgkmcnt(0)
	s_setprio 1
	v_mfma_f32_16x16x32_bf16 v[108:111], v[202:205], v[170:173], v[108:111]
	v_mfma_f32_16x16x32_bf16 v[100:103], v[228:231], v[170:173], v[100:103]
	v_mfma_f32_16x16x32_bf16 v[92:95], v[202:205], v[178:181], v[92:95]
	v_mfma_f32_16x16x32_bf16 v[84:87], v[228:231], v[178:181], v[84:87]
	v_mfma_f32_16x16x32_bf16 v[76:79], v[202:205], v[186:189], v[76:79]
	v_mfma_f32_16x16x32_bf16 v[72:75], v[228:231], v[186:189], v[72:75]
	v_mfma_f32_16x16x32_bf16 v[68:71], v[202:205], v[194:197], v[68:71]
	v_mfma_f32_16x16x32_bf16 v[64:67], v[228:231], v[194:197], v[64:67]
	v_mfma_f32_16x16x32_bf16 v[108:111], v[206:209], v[174:177], v[108:111]
	v_mfma_f32_16x16x32_bf16 v[100:103], v[232:235], v[174:177], v[100:103]
	v_mfma_f32_16x16x32_bf16 v[92:95], v[206:209], v[182:185], v[92:95]
	v_mfma_f32_16x16x32_bf16 v[84:87], v[232:235], v[182:185], v[84:87]
	v_mfma_f32_16x16x32_bf16 v[76:79], v[206:209], v[190:193], v[76:79]
	v_mfma_f32_16x16x32_bf16 v[72:75], v[232:235], v[190:193], v[72:75]
	v_mfma_f32_16x16x32_bf16 v[68:71], v[206:209], v[198:201], v[68:71]
	v_mfma_f32_16x16x32_bf16 v[64:67], v[232:235], v[198:201], v[64:67]
	s_setprio 0
	s_mov_b32 m0, s11
	v_lshl_add_u64 v[238:239], s[68:69], 0, v[128:129]
	s_barrier
	ds_read_b128 v[170:173], v139 offset:16384
	ds_read_b128 v[174:177], v139 offset:17408
	ds_read_b128 v[178:181], v139 offset:18432
	ds_read_b128 v[182:185], v139 offset:19456
	ds_read_b128 v[186:189], v139 offset:20480
	ds_read_b128 v[190:193], v139 offset:21504
	ds_read_b128 v[194:197], v139 offset:22528
	ds_read_b128 v[198:201], v139 offset:23552
	global_load_lds_dwordx4 v[238:239], off
	v_lshl_add_u64 v[240:241], s[68:69], 0, v[130:131]
	s_mov_b32 m0, s13
	s_nop 0
	global_load_lds_dwordx4 v[240:241], off
	s_barrier
	s_waitcnt lgkmcnt(0)
	s_setprio 1
	v_mfma_f32_16x16x32_bf16 v[60:63], v[154:157], v[170:173], v[60:63]
	v_mfma_f32_16x16x32_bf16 v[56:59], v[162:165], v[170:173], v[56:59]
	v_mfma_f32_16x16x32_bf16 v[52:55], v[154:157], v[178:181], v[52:55]
	v_mfma_f32_16x16x32_bf16 v[48:51], v[162:165], v[178:181], v[48:51]
	v_mfma_f32_16x16x32_bf16 v[36:39], v[154:157], v[186:189], v[36:39]
	v_mfma_f32_16x16x32_bf16 v[32:35], v[162:165], v[186:189], v[32:35]
	v_mfma_f32_16x16x32_bf16 v[20:23], v[154:157], v[194:197], v[20:23]
	v_mfma_f32_16x16x32_bf16 v[16:19], v[162:165], v[194:197], v[16:19]
	v_mfma_f32_16x16x32_bf16 v[60:63], v[158:161], v[174:177], v[60:63]
	v_mfma_f32_16x16x32_bf16 v[56:59], v[166:169], v[174:177], v[56:59]
	v_mfma_f32_16x16x32_bf16 v[52:55], v[158:161], v[182:185], v[52:55]
	v_mfma_f32_16x16x32_bf16 v[48:51], v[166:169], v[182:185], v[48:51]
	v_mfma_f32_16x16x32_bf16 v[36:39], v[158:161], v[190:193], v[36:39]
	v_mfma_f32_16x16x32_bf16 v[32:35], v[166:169], v[190:193], v[32:35]
	v_mfma_f32_16x16x32_bf16 v[20:23], v[158:161], v[198:201], v[20:23]
	v_mfma_f32_16x16x32_bf16 v[16:19], v[166:169], v[198:201], v[16:19]
	s_setprio 0
	s_barrier
	s_add_u32 s18, s0, 0x100000
	s_addc_u32 s19, s1, 0
	s_add_i32 s2, s30, s20
	v_lshl_add_u64 v[154:155], s[18:19], 0, v[140:141]
	s_mov_b32 m0, s2
	s_nop 0
	global_load_lds_dwordx4 v[154:155], off
	v_lshl_add_u64 v[154:155], s[18:19], 0, v[132:133]
	s_add_i32 m0, s2, 0x2000
	s_nop 0
	global_load_lds_dwordx4 v[154:155], off
	s_waitcnt vmcnt(6)
	s_barrier
	s_setprio 1
	v_mfma_f32_16x16x32_bf16 v[44:47], v[202:205], v[170:173], v[44:47]
	v_mfma_f32_16x16x32_bf16 v[40:43], v[228:231], v[170:173], v[40:43]
	v_mfma_f32_16x16x32_bf16 v[28:31], v[202:205], v[178:181], v[28:31]
	v_mfma_f32_16x16x32_bf16 v[24:27], v[228:231], v[178:181], v[24:27]
	v_mfma_f32_16x16x32_bf16 v[12:15], v[202:205], v[186:189], v[12:15]
	v_mfma_f32_16x16x32_bf16 v[8:11], v[228:231], v[186:189], v[8:11]
	v_mfma_f32_16x16x32_bf16 v[4:7], v[202:205], v[194:197], v[4:7]
	v_mfma_f32_16x16x32_bf16 v[0:3], v[228:231], v[194:197], v[0:3]
	v_mfma_f32_16x16x32_bf16 v[44:47], v[206:209], v[174:177], v[44:47]
	v_mfma_f32_16x16x32_bf16 v[40:43], v[232:235], v[174:177], v[40:43]
	v_mfma_f32_16x16x32_bf16 v[28:31], v[206:209], v[182:185], v[28:31]
	v_mfma_f32_16x16x32_bf16 v[24:27], v[232:235], v[182:185], v[24:27]
	v_mfma_f32_16x16x32_bf16 v[12:15], v[206:209], v[190:193], v[12:15]
	v_mfma_f32_16x16x32_bf16 v[8:11], v[232:235], v[190:193], v[8:11]
	v_mfma_f32_16x16x32_bf16 v[4:7], v[206:209], v[198:201], v[4:7]
	v_mfma_f32_16x16x32_bf16 v[0:3], v[232:235], v[198:201], v[0:3]
	s_setprio 0
	s_add_i32 s2, 0, 0x18000
	v_add_u32_e32 v166, s2, v138
	s_barrier
	ds_read_b128 v[154:157], v166
	ds_read_b128 v[158:161], v166 offset:1024
	ds_read_b128 v[162:165], v166 offset:2048
	ds_read_b128 v[166:169], v166 offset:3072
	s_add_u32 s18, s68, 0x80000
	s_addc_u32 s19, s69, 0
	s_mov_b32 m0, s15
	v_lshl_add_u64 v[202:203], s[18:19], 0, v[128:129]
	ds_read_b128 v[170:173], v139 offset:32768
	ds_read_b128 v[174:177], v139 offset:33792
	ds_read_b128 v[178:181], v139 offset:34816
	ds_read_b128 v[182:185], v139 offset:35840
	ds_read_b128 v[186:189], v139 offset:36864
	ds_read_b128 v[190:193], v139 offset:37888
	ds_read_b128 v[194:197], v139 offset:38912
	ds_read_b128 v[198:201], v139 offset:39936
	global_load_lds_dwordx4 v[202:203], off
	v_lshl_add_u64 v[202:203], s[18:19], 0, v[130:131]
	s_mov_b32 m0, s21
	s_nop 0
	global_load_lds_dwordx4 v[202:203], off
	s_waitcnt lgkmcnt(8)
	s_barrier
	s_waitcnt lgkmcnt(0)
	s_setprio 1
	v_mfma_f32_16x16x32_bf16 v[124:127], v[154:157], v[170:173], v[124:127]
	v_mfma_f32_16x16x32_bf16 v[120:123], v[162:165], v[170:173], v[120:123]
	v_mfma_f32_16x16x32_bf16 v[116:119], v[154:157], v[178:181], v[116:119]
	v_mfma_f32_16x16x32_bf16 v[112:115], v[162:165], v[178:181], v[112:115]
	v_mfma_f32_16x16x32_bf16 v[104:107], v[154:157], v[186:189], v[104:107]
	v_mfma_f32_16x16x32_bf16 v[96:99], v[162:165], v[186:189], v[96:99]
	v_mfma_f32_16x16x32_bf16 v[88:91], v[154:157], v[194:197], v[88:91]
	v_mfma_f32_16x16x32_bf16 v[80:83], v[162:165], v[194:197], v[80:83]
	v_mfma_f32_16x16x32_bf16 v[124:127], v[158:161], v[174:177], v[124:127]
	v_mfma_f32_16x16x32_bf16 v[120:123], v[166:169], v[174:177], v[120:123]
	v_mfma_f32_16x16x32_bf16 v[116:119], v[158:161], v[182:185], v[116:119]
	v_mfma_f32_16x16x32_bf16 v[112:115], v[166:169], v[182:185], v[112:115]
	v_mfma_f32_16x16x32_bf16 v[104:107], v[158:161], v[190:193], v[104:107]
	v_mfma_f32_16x16x32_bf16 v[96:99], v[166:169], v[190:193], v[96:99]
	v_mfma_f32_16x16x32_bf16 v[88:91], v[158:161], v[198:201], v[88:91]
	v_mfma_f32_16x16x32_bf16 v[80:83], v[166:169], v[198:201], v[80:83]
	s_setprio 0
	s_barrier
	s_add_i32 s18, 0, 0x1c000
	s_add_i32 s2, s2, s20
	v_add_u32_e32 v232, s18, v138
	v_lshl_add_u64 v[210:211], v[210:211], 0, s[82:83]
	s_mov_b32 m0, s2
	ds_read_b128 v[202:205], v232
	ds_read_b128 v[206:209], v232 offset:1024
	ds_read_b128 v[228:231], v232 offset:2048
	ds_read_b128 v[232:235], v232 offset:3072
	global_load_lds_dwordx4 v[210:211], off
	v_lshl_add_u64 v[210:211], v[236:237], 0, s[82:83]
	s_add_i32 m0, s2, 0x2000
	s_nop 0
	global_load_lds_dwordx4 v[210:211], off
	s_barrier
	s_waitcnt lgkmcnt(0)
	s_setprio 1
	v_mfma_f32_16x16x32_bf16 v[108:111], v[202:205], v[170:173], v[108:111]
	v_mfma_f32_16x16x32_bf16 v[100:103], v[228:231], v[170:173], v[100:103]
	v_mfma_f32_16x16x32_bf16 v[92:95], v[202:205], v[178:181], v[92:95]
	v_mfma_f32_16x16x32_bf16 v[84:87], v[228:231], v[178:181], v[84:87]
	v_mfma_f32_16x16x32_bf16 v[76:79], v[202:205], v[186:189], v[76:79]
	v_mfma_f32_16x16x32_bf16 v[72:75], v[228:231], v[186:189], v[72:75]
	v_mfma_f32_16x16x32_bf16 v[68:71], v[202:205], v[194:197], v[68:71]
	v_mfma_f32_16x16x32_bf16 v[64:67], v[228:231], v[194:197], v[64:67]
	v_mfma_f32_16x16x32_bf16 v[108:111], v[206:209], v[174:177], v[108:111]
	v_mfma_f32_16x16x32_bf16 v[100:103], v[232:235], v[174:177], v[100:103]
	v_mfma_f32_16x16x32_bf16 v[92:95], v[206:209], v[182:185], v[92:95]
	v_mfma_f32_16x16x32_bf16 v[84:87], v[232:235], v[182:185], v[84:87]
	v_mfma_f32_16x16x32_bf16 v[76:79], v[206:209], v[190:193], v[76:79]
	v_mfma_f32_16x16x32_bf16 v[72:75], v[232:235], v[190:193], v[72:75]
	v_mfma_f32_16x16x32_bf16 v[68:71], v[206:209], v[198:201], v[68:71]
	v_mfma_f32_16x16x32_bf16 v[64:67], v[232:235], v[198:201], v[64:67]
	s_setprio 0
	s_mov_b32 m0, s59
	v_lshl_add_u64 v[210:211], v[238:239], 0, s[82:83]
	s_barrier
	ds_read_b128 v[170:173], v139 offset:49152
	ds_read_b128 v[174:177], v139 offset:50176
	ds_read_b128 v[178:181], v139 offset:51200
	ds_read_b128 v[182:185], v139 offset:52224
	ds_read_b128 v[186:189], v139 offset:53248
	ds_read_b128 v[190:193], v139 offset:54272
	ds_read_b128 v[194:197], v139 offset:55296
	ds_read_b128 v[198:201], v139 offset:56320
	global_load_lds_dwordx4 v[210:211], off
	v_lshl_add_u64 v[210:211], v[240:241], 0, s[82:83]
	s_mov_b32 m0, s71
	s_nop 0
	global_load_lds_dwordx4 v[210:211], off
	s_barrier
	s_waitcnt lgkmcnt(0)
	s_setprio 1
	v_mfma_f32_16x16x32_bf16 v[60:63], v[154:157], v[170:173], v[60:63]
	v_mfma_f32_16x16x32_bf16 v[56:59], v[162:165], v[170:173], v[56:59]
	v_mfma_f32_16x16x32_bf16 v[52:55], v[154:157], v[178:181], v[52:55]
	v_mfma_f32_16x16x32_bf16 v[48:51], v[162:165], v[178:181], v[48:51]
	v_mfma_f32_16x16x32_bf16 v[36:39], v[154:157], v[186:189], v[36:39]
	v_mfma_f32_16x16x32_bf16 v[32:35], v[162:165], v[186:189], v[32:35]
	v_mfma_f32_16x16x32_bf16 v[20:23], v[154:157], v[194:197], v[20:23]
	v_mfma_f32_16x16x32_bf16 v[16:19], v[162:165], v[194:197], v[16:19]
	v_mfma_f32_16x16x32_bf16 v[60:63], v[158:161], v[174:177], v[60:63]
	v_mfma_f32_16x16x32_bf16 v[56:59], v[166:169], v[174:177], v[56:59]
	v_mfma_f32_16x16x32_bf16 v[52:55], v[158:161], v[182:185], v[52:55]
	v_mfma_f32_16x16x32_bf16 v[48:51], v[166:169], v[182:185], v[48:51]
	v_mfma_f32_16x16x32_bf16 v[36:39], v[158:161], v[190:193], v[36:39]
	v_mfma_f32_16x16x32_bf16 v[32:35], v[166:169], v[190:193], v[32:35]
	v_mfma_f32_16x16x32_bf16 v[20:23], v[158:161], v[198:201], v[20:23]
	v_mfma_f32_16x16x32_bf16 v[16:19], v[166:169], v[198:201], v[16:19]
	s_setprio 0
	s_barrier
	s_add_u32 s0, s0, 0x100080
	s_addc_u32 s1, s1, 0
	s_add_i32 s2, s18, s20
	v_lshl_add_u64 v[154:155], s[0:1], 0, v[140:141]
	s_mov_b32 m0, s2
	s_nop 0
	global_load_lds_dwordx4 v[154:155], off
	v_lshl_add_u64 v[154:155], s[0:1], 0, v[132:133]
	s_add_i32 m0, s2, 0x2000
	s_nop 0
	global_load_lds_dwordx4 v[154:155], off
	s_waitcnt vmcnt(6)
	s_barrier
	s_setprio 1
	v_mfma_f32_16x16x32_bf16 v[44:47], v[202:205], v[170:173], v[44:47]
	v_mfma_f32_16x16x32_bf16 v[40:43], v[228:231], v[170:173], v[40:43]
	v_mfma_f32_16x16x32_bf16 v[28:31], v[202:205], v[178:181], v[28:31]
	v_mfma_f32_16x16x32_bf16 v[24:27], v[228:231], v[178:181], v[24:27]
	v_mfma_f32_16x16x32_bf16 v[12:15], v[202:205], v[186:189], v[12:15]
	v_mfma_f32_16x16x32_bf16 v[8:11], v[228:231], v[186:189], v[8:11]
	v_mfma_f32_16x16x32_bf16 v[4:7], v[202:205], v[194:197], v[4:7]
	v_mfma_f32_16x16x32_bf16 v[0:3], v[228:231], v[194:197], v[0:3]
	v_mfma_f32_16x16x32_bf16 v[44:47], v[206:209], v[174:177], v[44:47]
	v_mfma_f32_16x16x32_bf16 v[40:43], v[232:235], v[174:177], v[40:43]
	v_mfma_f32_16x16x32_bf16 v[28:31], v[206:209], v[182:185], v[28:31]
	v_mfma_f32_16x16x32_bf16 v[24:27], v[232:235], v[182:185], v[24:27]
	v_mfma_f32_16x16x32_bf16 v[12:15], v[206:209], v[190:193], v[12:15]
	v_mfma_f32_16x16x32_bf16 v[8:11], v[232:235], v[190:193], v[8:11]
	v_mfma_f32_16x16x32_bf16 v[4:7], v[206:209], v[198:201], v[4:7]
	v_mfma_f32_16x16x32_bf16 v[0:3], v[232:235], v[198:201], v[0:3]
	s_setprio 0
	s_add_i32 s45, s45, 2
	s_add_u32 s17, s17, 0x100
	s_addc_u32 s41, s41, 0
	s_add_u32 s66, s66, 0x100
	s_addc_u32 s67, s67, 0
	s_cmp_gt_u32 s45, 29
	s_barrier
	s_cbranch_scc0 .LBB0_169
	s_lshl_b32 s0, s10, 11
	s_lshl_b32 s1, s14, 8
	s_add_i32 s0, s0, s57
	v_mbcnt_lo_u32_b32 v155, -1, 0
	v_mbcnt_hi_u32_b32 v155, -1, v155
	s_lshl_b32 s2, s12, 8
	v_ashrrev_i32_e32 v154, 2, v155
	s_add_i32 s0, s0, s1
	v_and_b32_e32 v154, -4, v154
	s_or_b32 s2, s2, s58
	v_and_or_b32 v156, v155, 15, s0
	v_add_u32_e32 v154, s2, v154
	v_ashrrev_i32_e32 v157, 31, v156
	v_ashrrev_i32_e32 v155, 31, v154
	v_lshlrev_b64 v[158:159], 12, v[156:157]
	v_lshl_add_u64 v[158:159], s[26:27], 0, v[158:159]
	v_lshlrev_b64 v[154:155], 2, v[154:155]
	v_lshl_add_u64 v[158:159], v[158:159], 0, v[154:155]
	flat_store_dwordx4 v[158:159], v[124:127]
	flat_store_dwordx4 v[158:159], v[120:123] offset:64
	flat_store_dwordx4 v[158:159], v[108:111] offset:512
	flat_store_dwordx4 v[158:159], v[100:103] offset:576
	s_mov_b64 s[0:1], 0x80000
	s_mov_b32 s10, s16
	v_or_b32_e32 v100, 16, v156
	v_ashrrev_i32_e32 v101, 31, v100
	v_lshlrev_b64 v[100:101], 12, v[100:101]
	v_lshl_add_u64 v[100:101], s[26:27], 0, v[100:101]
	v_lshl_add_u64 v[100:101], v[100:101], 0, v[154:155]
	flat_store_dwordx4 v[100:101], v[116:119]
	flat_store_dwordx4 v[100:101], v[112:115] offset:64
	flat_store_dwordx4 v[100:101], v[92:95] offset:512
	flat_store_dwordx4 v[100:101], v[84:87] offset:576
	s_mov_b32 s12, s40
	s_mov_b32 s14, s44
	v_or_b32_e32 v84, 32, v156
	v_ashrrev_i32_e32 v85, 31, v84
	v_lshlrev_b64 v[84:85], 12, v[84:85]
	v_lshl_add_u64 v[84:85], s[26:27], 0, v[84:85]
	v_lshl_add_u64 v[84:85], v[84:85], 0, v[154:155]
	flat_store_dwordx4 v[84:85], v[104:107]
	flat_store_dwordx4 v[84:85], v[96:99] offset:64
	flat_store_dwordx4 v[84:85], v[76:79] offset:512
	flat_store_dwordx4 v[84:85], v[72:75] offset:576
	s_mov_b64 s[66:67], s[64:65]
	s_nop 0
	v_or_b32_e32 v72, 48, v156
	v_ashrrev_i32_e32 v73, 31, v72
	v_lshlrev_b64 v[72:73], 12, v[72:73]
	v_lshl_add_u64 v[72:73], s[26:27], 0, v[72:73]
	v_lshl_add_u64 v[72:73], v[72:73], 0, v[154:155]
	flat_store_dwordx4 v[72:73], v[88:91]
	flat_store_dwordx4 v[72:73], v[80:83] offset:64
	flat_store_dwordx4 v[72:73], v[68:71] offset:512
	flat_store_dwordx4 v[72:73], v[64:67] offset:576
	s_nop 1
	v_lshl_add_u64 v[64:65], v[158:159], 0, s[0:1]
	s_mov_b32 s0, 0x80000
	v_add_co_u32_e32 v66, vcc, s0, v158
	s_mov_b64 s[0:1], 0x90000
	s_nop 0
	v_addc_co_u32_e32 v67, vcc, 0, v159, vcc
	flat_store_dwordx4 v[66:67], v[60:63]
	flat_store_dwordx4 v[64:65], v[56:59] offset:64
	flat_store_dwordx4 v[64:65], v[44:47] offset:512
	flat_store_dwordx4 v[64:65], v[40:43] offset:576
	s_nop 1
	v_lshl_add_u64 v[40:41], v[158:159], 0, s[0:1]
	s_mov_b32 s0, 0x90000
	v_add_co_u32_e32 v42, vcc, s0, v158
	s_mov_b64 s[0:1], 0xa0000
	s_nop 0
	v_addc_co_u32_e32 v43, vcc, 0, v159, vcc
	flat_store_dwordx4 v[42:43], v[52:55]
	flat_store_dwordx4 v[40:41], v[48:51] offset:64
	flat_store_dwordx4 v[40:41], v[28:31] offset:512
	flat_store_dwordx4 v[40:41], v[24:27] offset:576
	s_nop 1
	v_lshl_add_u64 v[24:25], v[158:159], 0, s[0:1]
	s_mov_b32 s0, 0xa0000
	v_add_co_u32_e32 v26, vcc, s0, v158
	s_mov_b64 s[0:1], 0xb0000
	s_nop 0
	v_addc_co_u32_e32 v27, vcc, 0, v159, vcc
	flat_store_dwordx4 v[26:27], v[36:39]
	flat_store_dwordx4 v[24:25], v[32:35] offset:64
	flat_store_dwordx4 v[24:25], v[12:15] offset:512
	flat_store_dwordx4 v[24:25], v[8:11] offset:576
	s_nop 1
	v_add_co_u32_e32 v10, vcc, 0xb0000, v158
	v_lshl_add_u64 v[8:9], v[158:159], 0, s[0:1]
	s_nop 0
	v_addc_co_u32_e32 v11, vcc, 0, v159, vcc
	s_and_b64 vcc, exec, s[6:7]
	s_mov_b64 s[0:1], s[8:9]
	flat_store_dwordx4 v[10:11], v[20:23]
	flat_store_dwordx4 v[8:9], v[16:19] offset:64
	flat_store_dwordx4 v[8:9], v[4:7] offset:512
	flat_store_dwordx4 v[8:9], v[0:3] offset:576
	s_cbranch_vccz .LBB0_160
	s_waitcnt vmcnt(0)
	s_cmpk_gt_u32 s51, 0xff
	s_cbranch_scc1 .LBB0_173
	s_barrier
